# v044 + grid-barrier poll back-off: s_sleep 1 to s_sleep 3 in all spin loops, to cut L2 polling pressure on the leader path
# speedup vs baseline: 1.0025x; 1.0025x over previous
.LBB0_247:
	global_load_dword v17, v18, s[78:79] offset:1024 sc1
	global_load_dword v2, v18, s[78:79] offset:1280 sc1
	global_load_dword v3, v18, s[78:79] offset:1536 sc1
	global_load_dword v4, v18, s[78:79] offset:1792 sc1
	global_load_dword v5, v18, s[78:79] offset:2048 sc1
	global_load_dword v6, v18, s[78:79] offset:2304 sc1
	global_load_dword v7, v18, s[78:79] offset:2560 sc1
	global_load_dword v8, v18, s[78:79] offset:2816 sc1
	global_load_dword v9, v18, s[78:79] offset:3072 sc1
	global_load_dword v10, v18, s[78:79] offset:3328 sc1
	global_load_dword v11, v18, s[78:79] offset:3584 sc1
	global_load_dword v12, v18, s[78:79] offset:3840 sc1
	global_load_dword v13, v18, s[4:5] sc1
	global_load_dword v14, v18, s[6:7] sc1
	global_load_dword v15, v18, s[10:11] sc1
	global_load_dword v16, v18, s[12:13] sc1
	s_mov_b64 s[16:17], -1
	s_mov_b64 s[20:21], -1
	s_waitcnt vmcnt(14)
	v_add_u32_e32 v19, v2, v17
	s_waitcnt vmcnt(13)
	v_add_u32_e32 v19, v19, v3
	s_waitcnt vmcnt(12)
	v_add_u32_e32 v19, v19, v4
	s_waitcnt vmcnt(11)
	v_add_u32_e32 v19, v19, v5
	s_waitcnt vmcnt(10)
	v_add_u32_e32 v19, v19, v6
	s_waitcnt vmcnt(9)
	v_add_u32_e32 v19, v19, v7
	s_waitcnt vmcnt(8)
	v_add_u32_e32 v19, v19, v8
	s_waitcnt vmcnt(7)
	v_add_u32_e32 v19, v19, v9
	s_waitcnt vmcnt(6)
	v_add_u32_e32 v19, v19, v10
	s_waitcnt vmcnt(5)
	v_add_u32_e32 v19, v19, v11
	s_waitcnt vmcnt(4)
	v_add_u32_e32 v19, v19, v12
	s_waitcnt vmcnt(3)
	v_add_u32_e32 v19, v19, v13
	s_waitcnt vmcnt(2)
	v_add_u32_e32 v19, v19, v14
	s_waitcnt vmcnt(1)
	v_add_u32_e32 v19, v19, v15
	s_waitcnt vmcnt(0)
	v_add_u32_e32 v19, v19, v16
	v_cmp_eq_u32_e32 vcc, s26, v19
	s_cbranch_vccnz .LBB0_246
	s_and_b32 s16, s27, 0xff
	s_cmp_eq_u32 s16, 0
	s_mov_b64 s[16:17], -1
	s_mov_b64 s[24:25], -1
	s_sleep 3
	s_cbranch_scc1 .LBB0_251
	s_and_b64 vcc, exec, s[24:25]
	s_cbranch_vccz .LBB0_246

.LBB0_263:
	s_and_b32 s26, s30, 0xff
	s_mov_b64 s[24:25], -1
	s_cmp_lg_u32 s26, 0
	s_mov_b64 s[28:29], -1
	s_sleep 3
	s_cbranch_scc0 .LBB0_266
	s_and_b64 vcc, exec, s[28:29]
	s_cbranch_vccz .LBB0_262

.LBB0_280:
	s_and_b32 s26, s34, 0xff
	s_cmp_lg_u32 s26, 0
	s_mov_b64 s[28:29], -1
	s_sleep 3
	s_cbranch_scc0 .LBB0_283
	s_mov_b64 s[30:31], -1
	s_and_b64 vcc, exec, s[28:29]
	s_cbranch_vccz .LBB0_279

.LBB0_342:
	global_load_dword v17, v18, s[78:79] offset:1024 sc1
	global_load_dword v2, v18, s[78:79] offset:1280 sc1
	global_load_dword v3, v18, s[78:79] offset:1536 sc1
	global_load_dword v4, v18, s[78:79] offset:1792 sc1
	global_load_dword v5, v18, s[78:79] offset:2048 sc1
	global_load_dword v6, v18, s[78:79] offset:2304 sc1
	global_load_dword v7, v18, s[78:79] offset:2560 sc1
	global_load_dword v8, v18, s[78:79] offset:2816 sc1
	global_load_dword v9, v18, s[78:79] offset:3072 sc1
	global_load_dword v10, v18, s[78:79] offset:3328 sc1
	global_load_dword v11, v18, s[78:79] offset:3584 sc1
	global_load_dword v12, v18, s[78:79] offset:3840 sc1
	global_load_dword v13, v18, s[4:5] sc1
	global_load_dword v14, v18, s[6:7] sc1
	global_load_dword v15, v18, s[8:9] sc1
	global_load_dword v16, v18, s[10:11] sc1
	s_mov_b64 s[12:13], -1
	s_mov_b64 s[16:17], -1
	s_waitcnt vmcnt(14)
	v_add_u32_e32 v19, v2, v17
	s_waitcnt vmcnt(13)
	v_add_u32_e32 v19, v19, v3
	s_waitcnt vmcnt(12)
	v_add_u32_e32 v19, v19, v4
	s_waitcnt vmcnt(11)
	v_add_u32_e32 v19, v19, v5
	s_waitcnt vmcnt(10)
	v_add_u32_e32 v19, v19, v6
	s_waitcnt vmcnt(9)
	v_add_u32_e32 v19, v19, v7
	s_waitcnt vmcnt(8)
	v_add_u32_e32 v19, v19, v8
	s_waitcnt vmcnt(7)
	v_add_u32_e32 v19, v19, v9
	s_waitcnt vmcnt(6)
	v_add_u32_e32 v19, v19, v10
	s_waitcnt vmcnt(5)
	v_add_u32_e32 v19, v19, v11
	s_waitcnt vmcnt(4)
	v_add_u32_e32 v19, v19, v12
	s_waitcnt vmcnt(3)
	v_add_u32_e32 v19, v19, v13
	s_waitcnt vmcnt(2)
	v_add_u32_e32 v19, v19, v14
	s_waitcnt vmcnt(1)
	v_add_u32_e32 v19, v19, v15
	s_waitcnt vmcnt(0)
	v_add_u32_e32 v19, v19, v16
	v_cmp_eq_u32_e32 vcc, s22, v19
	s_cbranch_vccnz .LBB0_341
	s_and_b32 s12, s23, 0xff
	s_cmp_eq_u32 s12, 0
	s_mov_b64 s[12:13], -1
	s_mov_b64 s[20:21], -1
	s_sleep 3
	s_cbranch_scc1 .LBB0_346
	s_and_b64 vcc, exec, s[20:21]
	s_cbranch_vccz .LBB0_341

.LBB0_358:
	s_and_b32 s22, s26, 0xff
	s_mov_b64 s[20:21], -1
	s_cmp_lg_u32 s22, 0
	s_mov_b64 s[24:25], -1
	s_sleep 3
	s_cbranch_scc0 .LBB0_361
	s_and_b64 vcc, exec, s[24:25]
	s_cbranch_vccz .LBB0_357

.LBB0_375:
	s_and_b32 s22, s28, 0xff
	s_cmp_lg_u32 s22, 0
	s_mov_b64 s[24:25], -1
	s_sleep 3
	s_cbranch_scc0 .LBB0_378
	s_mov_b64 s[26:27], -1
	s_and_b64 vcc, exec, s[24:25]
	s_cbranch_vccz .LBB0_374

.LBB0_1399:
	global_load_dword v17, v18, s[78:79] offset:1024 sc1
	global_load_dword v2, v18, s[78:79] offset:1280 sc1
	global_load_dword v3, v18, s[78:79] offset:1536 sc1
	global_load_dword v4, v18, s[78:79] offset:1792 sc1
	global_load_dword v5, v18, s[78:79] offset:2048 sc1
	global_load_dword v6, v18, s[78:79] offset:2304 sc1
	global_load_dword v7, v18, s[78:79] offset:2560 sc1
	global_load_dword v8, v18, s[78:79] offset:2816 sc1
	global_load_dword v9, v18, s[78:79] offset:3072 sc1
	global_load_dword v10, v18, s[78:79] offset:3328 sc1
	global_load_dword v11, v18, s[78:79] offset:3584 sc1
	global_load_dword v12, v18, s[78:79] offset:3840 sc1
	global_load_dword v13, v18, s[4:5] sc1
	global_load_dword v14, v18, s[6:7] sc1
	global_load_dword v15, v18, s[8:9] sc1
	global_load_dword v16, v18, s[10:11] sc1
	s_mov_b64 s[12:13], -1
	s_mov_b64 s[14:15], -1
	s_waitcnt vmcnt(14)
	v_add_u32_e32 v19, v2, v17
	s_waitcnt vmcnt(13)
	v_add_u32_e32 v19, v19, v3
	s_waitcnt vmcnt(12)
	v_add_u32_e32 v19, v19, v4
	s_waitcnt vmcnt(11)
	v_add_u32_e32 v19, v19, v5
	s_waitcnt vmcnt(10)
	v_add_u32_e32 v19, v19, v6
	s_waitcnt vmcnt(9)
	v_add_u32_e32 v19, v19, v7
	s_waitcnt vmcnt(8)
	v_add_u32_e32 v19, v19, v8
	s_waitcnt vmcnt(7)
	v_add_u32_e32 v19, v19, v9
	s_waitcnt vmcnt(6)
	v_add_u32_e32 v19, v19, v10
	s_waitcnt vmcnt(5)
	v_add_u32_e32 v19, v19, v11
	s_waitcnt vmcnt(4)
	v_add_u32_e32 v19, v19, v12
	s_waitcnt vmcnt(3)
	v_add_u32_e32 v19, v19, v13
	s_waitcnt vmcnt(2)
	v_add_u32_e32 v19, v19, v14
	s_waitcnt vmcnt(1)
	v_add_u32_e32 v19, v19, v15
	s_waitcnt vmcnt(0)
	v_add_u32_e32 v19, v19, v16
	v_cmp_eq_u32_e32 vcc, s18, v19
	s_cbranch_vccnz .LBB0_1398
	s_and_b32 s12, s19, 0xff
	s_cmp_eq_u32 s12, 0
	s_mov_b64 s[12:13], -1
	s_mov_b64 s[16:17], -1
	s_sleep 3
	s_cbranch_scc1 .LBB0_1403
	s_and_b64 vcc, exec, s[16:17]
	s_cbranch_vccz .LBB0_1398

.LBB0_1415:
	s_and_b32 s18, s22, 0xff
	s_mov_b64 s[16:17], -1
	s_cmp_lg_u32 s18, 0
	s_mov_b64 s[20:21], -1
	s_sleep 3
	s_cbranch_scc0 .LBB0_1418
	s_and_b64 vcc, exec, s[20:21]
	s_cbranch_vccz .LBB0_1414

.LBB0_1432:
	s_and_b32 s18, s24, 0xff
	s_cmp_lg_u32 s18, 0
	s_mov_b64 s[20:21], -1
	s_sleep 3
	s_cbranch_scc0 .LBB0_1435
	s_mov_b64 s[22:23], -1
	s_and_b64 vcc, exec, s[20:21]
	s_cbranch_vccz .LBB0_1431

.LBB0_3949:
	global_load_dword v15, v16, s[78:79] offset:1024 sc1
	global_load_dword v0, v16, s[78:79] offset:1280 sc1
	global_load_dword v1, v16, s[78:79] offset:1536 sc1
	global_load_dword v2, v16, s[78:79] offset:1792 sc1
	global_load_dword v3, v16, s[78:79] offset:2048 sc1
	global_load_dword v4, v16, s[78:79] offset:2304 sc1
	global_load_dword v5, v16, s[78:79] offset:2560 sc1
	global_load_dword v6, v16, s[78:79] offset:2816 sc1
	global_load_dword v7, v16, s[78:79] offset:3072 sc1
	global_load_dword v8, v16, s[78:79] offset:3328 sc1
	global_load_dword v9, v16, s[78:79] offset:3584 sc1
	global_load_dword v10, v16, s[78:79] offset:3840 sc1
	global_load_dword v11, v16, s[2:3] sc1
	global_load_dword v12, v16, s[4:5] sc1
	global_load_dword v13, v16, s[6:7] sc1
	global_load_dword v14, v16, s[8:9] sc1
	s_mov_b64 s[10:11], -1
	s_mov_b64 s[12:13], -1
	s_waitcnt vmcnt(14)
	v_add_u32_e32 v17, v0, v15
	s_waitcnt vmcnt(13)
	v_add_u32_e32 v17, v17, v1
	s_waitcnt vmcnt(12)
	v_add_u32_e32 v17, v17, v2
	s_waitcnt vmcnt(11)
	v_add_u32_e32 v17, v17, v3
	s_waitcnt vmcnt(10)
	v_add_u32_e32 v17, v17, v4
	s_waitcnt vmcnt(9)
	v_add_u32_e32 v17, v17, v5
	s_waitcnt vmcnt(8)
	v_add_u32_e32 v17, v17, v6
	s_waitcnt vmcnt(7)
	v_add_u32_e32 v17, v17, v7
	s_waitcnt vmcnt(6)
	v_add_u32_e32 v17, v17, v8
	s_waitcnt vmcnt(5)
	v_add_u32_e32 v17, v17, v9
	s_waitcnt vmcnt(4)
	v_add_u32_e32 v17, v17, v10
	s_waitcnt vmcnt(3)
	v_add_u32_e32 v17, v17, v11
	s_waitcnt vmcnt(2)
	v_add_u32_e32 v17, v17, v12
	s_waitcnt vmcnt(1)
	v_add_u32_e32 v17, v17, v13
	s_waitcnt vmcnt(0)
	v_add_u32_e32 v17, v17, v14
	v_cmp_eq_u32_e32 vcc, s16, v17
	s_cbranch_vccnz .LBB0_3948
	s_and_b32 s10, s17, 0xff
	s_cmp_eq_u32 s10, 0
	s_mov_b64 s[10:11], -1
	s_mov_b64 s[14:15], -1
	s_sleep 3
	s_cbranch_scc1 .LBB0_3953
	s_and_b64 vcc, exec, s[14:15]
	s_cbranch_vccz .LBB0_3948

.LBB0_3965:
	s_and_b32 s16, s20, 0xff
	s_mov_b64 s[14:15], -1
	s_cmp_lg_u32 s16, 0
	s_mov_b64 s[18:19], -1
	s_sleep 3
	s_cbranch_scc0 .LBB0_3968
	s_and_b64 vcc, exec, s[18:19]
	s_cbranch_vccz .LBB0_3964

.LBB0_3982:
	s_and_b32 s16, s22, 0xff
	s_cmp_lg_u32 s16, 0
	s_mov_b64 s[18:19], -1
	s_sleep 3
	s_cbranch_scc0 .LBB0_3985
	s_mov_b64 s[20:21], -1
	s_and_b64 vcc, exec, s[18:19]
	s_cbranch_vccz .LBB0_3981
